# static s_setprio 1 for waves 4-7 of each workgroup during the two attention items (reset before the SSD item)
# speedup vs baseline: 1.0046x; 1.0046x over previous
.LBB0_1254:
	s_andn2_b64 vcc, exec, s[6:7]
	s_cbranch_vccnz .LBB0_2256
	s_mov_b64 s[4:5], s[0:1]
	s_load_dwordx2 s[90:91], s[4:5], 0xd8
	v_readfirstlane_b32 s2, v180
	s_ashr_i32 s2, s2, 6
	s_cmp_ge_u32 s2, 4
	s_cbranch_scc0 att_prio_skip
	s_setprio 1
att_prio_skip:
	v_and_b32_e32 v181, 63, v180
	s_mul_i32 s18, s2, 0x4500
	v_or_b32_e32 v221, 0xffffffc0, v181
	v_lshlrev_b32_e32 v222, 2, v181
	s_add_i32 s96, s18, 0
	v_add_u32_e32 v2, s96, v222
	s_mov_b64 s[6:7], 0
	v_mov_b32_e32 v3, v221

.LBB0_2256:
	s_setprio 0
	v_readlane_b32 s4, v243, 30
	v_readlane_b32 s5, v243, 31
	s_andn2_b64 vcc, exec, s[4:5]
	s_barrier
	s_cbranch_vccnz .LBB0_2363
	v_lshlrev_b32_e32 v124, 2, v180
	v_readlane_b32 s2, v242, 4
	v_bfe_u32 v3, v180, 4, 2
	v_ashrrev_i32_e32 v68, 4, v180
	v_add_u32_e32 v125, s2, v124
	s_movk_i32 s2, 0x280
	v_cmp_gt_i32_e64 s[6:7], s2, v180
	s_movk_i32 s2, 0x100
	v_max_i32_e32 v7, 0x80, v180
	v_cmp_gt_i32_e64 s[8:9], s2, v68
	v_lshlrev_b32_e32 v2, 3, v3
	v_readlane_b32 s2, v242, 7
	v_sub_u32_e32 v7, v7, v180
	v_add_u32_e32 v7, 0x1ff, v7
	v_add_u32_e32 v70, s2, v2
	s_movk_i32 s2, 0x1ff
	v_and_b32_e32 v71, 15, v180
	v_lshrrev_b32_e32 v9, 9, v7
	v_cmp_lt_u32_e64 s[12:13], s2, v7
	s_movk_i32 s2, 0x110
	v_lshlrev_b32_e32 v130, 5, v3
	v_readlane_b32 s5, v242, 6
	v_add_u32_e32 v9, 1, v9
	v_mul_lo_u32 v7, v68, s2
	v_lshlrev_b32_e32 v72, 4, v71
	v_add_u32_e32 v131, s5, v130
	v_lshlrev_b32_e32 v4, 7, v71
	v_and_b32_e32 v133, 0xfffffe, v9
	v_add_u32_e32 v135, s5, v124
	v_add3_u32 v136, v7, v72, 0
	v_mul_lo_u32 v7, v68, s81
	v_readlane_b32 s5, v242, 8
	v_ashrrev_i32_e32 v67, 6, v180
	v_ashrrev_i32_e32 v64, 8, v180
	v_readlane_b32 s4, v242, 5
	v_and_b32_e32 v127, 0x7f, v180
	v_mul_i32_i24_e32 v5, -14, v71
	v_lshlrev_b32_e32 v132, 2, v3
	v_or_b32_e32 v6, 0x800, v4
	v_or_b32_e32 v8, 0x1000, v4
	v_or_b32_e32 v10, 0x1800, v4
	v_cmp_ne_u32_e64 s[14:15], v9, v133
	v_add3_u32 v137, v7, v72, s5
	v_and_b32_e32 v7, 0x400, v4
	v_lshlrev_b32_e32 v9, 2, v68
	v_lshlrev_b32_e32 v139, 4, v3
	v_mul_u32_u24_e32 v3, 0x420, v3
	v_readlane_b32 s34, v243, 56
	v_and_b32_e32 v66, 0xff, v180
	v_ashrrev_i32_e32 v65, 31, v64
	v_add_u32_e32 v126, s4, v124
	v_or_b32_e32 v128, 0x200, v127
	v_lshlrev_b32_e32 v129, 3, v71
	v_cmp_gt_i32_e64 s[10:11], 16, v67
	v_lshl_add_u32 v134, v133, 9, v180
	v_add_u32_e32 v181, 0x200, v180
	v_mov_b32_e32 v73, v11
	v_ashrrev_i32_e32 v69, 31, v68
	v_add3_u32 v138, v7, v9, s4
	v_mad_u32_u24 v140, v71, s2, v139
	v_or_b32_e32 v141, 19, v132
	v_add3_u32 v142, v5, v3, v72
	v_lshlrev_b32_e32 v74, 1, v4
	v_lshlrev_b32_e32 v76, 1, v6
	v_lshlrev_b32_e32 v78, 1, v8
	v_lshlrev_b32_e32 v80, 1, v10
	v_lshlrev_b32_e32 v82, 1, v2
	v_readlane_b32 s35, v243, 57
	s_mov_b32 s2, s73
	s_branch .LBB0_2259
